# C1b: DFT combine pass: second item's loads issued before the first consumer wait, byte-exact (all other addresses unchanged); on top of K1+R1+S1+Z1
# baseline (speedup 1.0000x reference)
; __device__ __forceinline__ u32x4 pack8(const f32x4& a, const f32x4& b) { u32x4 w; w.x = cvt_pk_bf16(a[0], a[1]); w.y = cvt_pk_bf16(a[2], a[3]); w.z = cvt_pk_bf16(b[0], b[1]); w.w = cvt_pk_bf16(b[2], b[3]); return w; }
; __device__ __forceinline__ void dft_combine(const Args& a, int gt, int NT, int lane, int gw, int NGW) {
;     ...
;     for (int idx0 = gt; idx0 < 1024 * 512; idx0 += 2 * NT) {
;         typedef _Float16 h8 __attribute__((ext_vector_type(8))); typedef float f8 __attribute__((ext_vector_type(8)));
;         f32x4 v[2][8]; int kk[2], bb[2], cc8[2]; bool okk[2];
; #pragma unroll
;         for (int u = 0; u < 2; ++u) {
;             const int idx = idx0 + u * NT; okk[u] = idx < 1024 * 512; const int id = okk[u] ? idx : idx0;
;             kk[u] = id >> 9; const int cc = id & 511; bb[u] = cc >> 6; cc8[u] = (cc & 63) * 8;
;             const _Float16* p = SL + (size_t)kk[u] * 4096 + bb[u] * 512 + cc8[u];
; #pragma unroll
;             for (int q = 0; q < 4; ++q) { const f8 t = __builtin_convertvector(*(const h8*)(p + q * SS), f8); v[u][2 * q] = (f32x4){t[0], t[1], t[2], t[3]}; v[u][2 * q + 1] = (f32x4){t[4], t[5], t[6], t[7]}; }
;         }
; #pragma unroll
;         for (int u = 0; u < 2; ++u) {
;             if (!okk[u]) continue;
;             const f32x4 P0 = v[u][0] + v[u][2], P1 = v[u][1] + v[u][3], Q0 = v[u][4] + v[u][6], Q1 = v[u][5] + v[u][7];
;             *(u32x4*)(MIXo + (size_t)(bb[u] * SEQ + kk[u]) * KMO + 512 + cc8[u]) = gm::pack8(P0 + Q0, P1 + Q1);
;             if (kk[u] > 0) *(u32x4*)(MIXo + (size_t)(bb[u] * SEQ + SEQ - kk[u]) * KMO + 512 + cc8[u]) = gm::pack8(P0 - Q0, P1 - Q1);
;         }
.LBB0_133:
	v_add_u32_e32 v39, s1, v0
	s_mov_b32 s5, 0x80000
	v_cmp_gt_i32_e64 s[34:35], s5, v39
	v_ashrrev_i32_e32 v20, 9, v0
	v_readlane_b32 s12, v252, 6
	v_cndmask_b32_e64 v6, v0, v39, s[34:35]
	v_ashrrev_i32_e32 v16, 9, v6
	v_ashrrev_i32_e32 v17, 31, v16
	v_bfe_u32 v40, v6, 6, 3
	v_lshlrev_b64 v[2:3], 13, v[16:17]
	v_readlane_b32 s13, v252, 7
	v_ashrrev_i32_e32 v21, 31, v20
	v_lshlrev_b32_e32 v80, 10, v40
	v_lshl_add_u64 v[2:3], s[12:13], 0, v[2:3]
	v_lshlrev_b64 v[4:5], 13, v[20:21]
	v_bfe_u32 v17, v0, 6, 3
	v_lshl_add_u64 v[2:3], v[2:3], 0, v[80:81]
	v_lshl_add_u64 v[4:5], s[12:13], 0, v[4:5]
	v_lshlrev_b32_e32 v80, 10, v17
	v_lshl_add_u64 v[0:1], v[4:5], 0, v[80:81]
	v_and_b32_e32 v4, 0x1f8, v38
	v_lshlrev_b32_e32 v80, 1, v4
	v_lshl_add_u64 v[0:1], v[0:1], 0, v[80:81]
	s_mov_b32 s12, 0x1800000
	v_add_co_u32_e32 v4, vcc, s12, v0
	s_mov_b32 s9, 0x1000000
	s_nop 0
	v_addc_co_u32_e32 v5, vcc, 0, v1, vcc
	global_load_dwordx4 v[22:25], v[4:5], off
	v_add_co_u32_e32 v4, vcc, s9, v0
	s_mov_b32 s5, 0x800000
	s_nop 0
	v_addc_co_u32_e32 v5, vcc, 0, v1, vcc
	global_load_dwordx4 v[26:29], v[4:5], off
	v_add_co_u32_e32 v4, vcc, s5, v0
	v_mov_b32_e32 v19, v81
	s_nop 0
	v_addc_co_u32_e32 v5, vcc, 0, v1, vcc
	global_load_dwordx4 v[30:33], v[4:5], off
	global_load_dwordx4 v[34:37], v[0:1], off
	v_lshlrev_b32_e32 v0, 3, v6
	v_and_b32_e32 v0, 0x1f8, v0
	v_lshlrev_b32_e32 v18, 1, v0
	v_lshl_add_u64 v[0:1], v[2:3], 0, v[18:19]
	v_add_co_u32_e32 v2, vcc, s5, v0
	v_lshlrev_b32_e32 v17, 11, v17
	s_nop 0
	v_addc_co_u32_e32 v3, vcc, 0, v1, vcc
	v_add_co_u32_e32 v4, vcc, s9, v0
	s_nop 1
	v_addc_co_u32_e32 v5, vcc, 0, v1, vcc
	v_add_co_u32_e32 v42, vcc, s12, v0
	global_load_dwordx4 v[12:15], v[0:1], off
	global_load_dwordx4 v[8:11], v[2:3], off
	v_addc_co_u32_e32 v43, vcc, 0, v1, vcc
	global_load_dwordx4 v[4:7], v[4:5], off
	s_nop 0
	global_load_dwordx4 v[0:3], v[42:43], off
	s_nop 0
	s_waitcnt vmcnt(7)
	v_cvt_f32_f16_e32 v44, v23
	v_cvt_f32_f16_sdwa v45, v23 dst_sel:DWORD dst_unused:UNUSED_PAD src0_sel:WORD_1
	v_cvt_f32_f16_e32 v42, v22
	v_cvt_f32_f16_sdwa v43, v22 dst_sel:DWORD dst_unused:UNUSED_PAD src0_sel:WORD_1
	v_cvt_f32_f16_e32 v46, v24
	v_cvt_f32_f16_sdwa v47, v24 dst_sel:DWORD dst_unused:UNUSED_PAD src0_sel:WORD_1
	v_cvt_f32_f16_e32 v48, v25
	v_cvt_f32_f16_sdwa v49, v25 dst_sel:DWORD dst_unused:UNUSED_PAD src0_sel:WORD_1
	s_waitcnt vmcnt(6)
	v_cvt_f32_f16_e32 v50, v26
	v_cvt_f32_f16_sdwa v51, v26 dst_sel:DWORD dst_unused:UNUSED_PAD src0_sel:WORD_1
	v_cvt_f32_f16_e32 v52, v27
	v_cvt_f32_f16_sdwa v53, v27 dst_sel:DWORD dst_unused:UNUSED_PAD src0_sel:WORD_1
	v_cvt_f32_f16_e32 v54, v28
	v_cvt_f32_f16_sdwa v55, v28 dst_sel:DWORD dst_unused:UNUSED_PAD src0_sel:WORD_1
	v_cvt_f32_f16_e32 v56, v29
	v_cvt_f32_f16_sdwa v57, v29 dst_sel:DWORD dst_unused:UNUSED_PAD src0_sel:WORD_1
	s_waitcnt vmcnt(5)
	v_cvt_f32_f16_e32 v28, v30
	v_cvt_f32_f16_sdwa v29, v30 dst_sel:DWORD dst_unused:UNUSED_PAD src0_sel:WORD_1
	v_cvt_f32_f16_e32 v26, v31
	v_cvt_f32_f16_sdwa v27, v31 dst_sel:DWORD dst_unused:UNUSED_PAD src0_sel:WORD_1
	v_cvt_f32_f16_e32 v24, v32
	v_cvt_f32_f16_sdwa v25, v32 dst_sel:DWORD dst_unused:UNUSED_PAD src0_sel:WORD_1
	v_cvt_f32_f16_e32 v22, v33
	v_cvt_f32_f16_sdwa v23, v33 dst_sel:DWORD dst_unused:UNUSED_PAD src0_sel:WORD_1
	s_waitcnt vmcnt(4)
	v_cvt_f32_f16_e32 v30, v34
	v_cvt_f32_f16_e32 v32, v35
	v_cvt_f32_f16_e32 v60, v37
	v_cvt_f32_f16_sdwa v61, v37 dst_sel:DWORD dst_unused:UNUSED_PAD src0_sel:WORD_1
	v_cvt_f32_f16_sdwa v33, v35 dst_sel:DWORD dst_unused:UNUSED_PAD src0_sel:WORD_1
	v_cvt_f32_f16_sdwa v31, v34 dst_sel:DWORD dst_unused:UNUSED_PAD src0_sel:WORD_1
	v_cvt_f32_f16_e32 v58, v36
	v_cvt_f32_f16_sdwa v59, v36 dst_sel:DWORD dst_unused:UNUSED_PAD src0_sel:WORD_1
	v_pk_add_f32 v[22:23], v[22:23], v[60:61]
	v_pk_add_f32 v[26:27], v[26:27], v[32:33]
	v_pk_add_f32 v[28:29], v[28:29], v[30:31]
	v_pk_add_f32 v[30:31], v[48:49], v[56:57]
	v_pk_add_f32 v[34:35], v[44:45], v[52:53]
	v_pk_add_f32 v[36:37], v[42:43], v[50:51]
	v_pk_add_f32 v[32:33], v[46:47], v[54:55]
	v_pk_add_f32 v[44:45], v[34:35], v[26:27]
	v_pk_add_f32 v[42:43], v[36:37], v[28:29]
	v_pk_add_f32 v[46:47], v[30:31], v[22:23]
	v_cvt_pk_bf16_f32 v42, v42, v43
	v_cvt_pk_bf16_f32 v43, v44, v45
	v_cvt_pk_bf16_f32 v45, v46, v47
	v_add_u32_e32 v46, v17, v20
	v_ashrrev_i32_e32 v47, 31, v46
	v_readlane_b32 s12, v252, 4
	v_pk_add_f32 v[24:25], v[24:25], v[58:59]
	v_lshlrev_b64 v[46:47], 11, v[46:47]
	v_readlane_b32 s13, v252, 5
	v_pk_add_f32 v[48:49], v[32:33], v[24:25]
	v_cmp_lt_i32_e32 vcc, 0, v20
	v_lshl_add_u64 v[46:47], s[12:13], 0, v[46:47]
	v_cvt_pk_bf16_f32 v44, v48, v49
	v_lshl_add_u64 v[46:47], v[46:47], 0, v[80:81]
	global_store_dwordx4 v[46:47], v[42:45], off offset:1024 sc1
	s_and_saveexec_b64 s[12:13], vcc
	s_cbranch_execz .LBB0_135
	v_sub_u32_e32 v17, v17, v20
	v_sub_f32_e32 v19, v27, v35
	v_sub_f32_e32 v21, v26, v34
	v_lshlrev_b32_e32 v20, 11, v17
	v_readlane_b32 s16, v252, 4
	v_sub_f32_e32 v27, v28, v36
	v_sub_f32_e32 v28, v23, v31
	v_cvt_pk_bf16_f32 v23, v21, v19
	v_ashrrev_i32_e32 v21, 31, v20
	v_readlane_b32 s17, v252, 5
	v_sub_f32_e32 v26, v29, v37
	v_sub_f32_e32 v29, v22, v30
	v_lshl_add_u64 v[20:21], s[16:17], 0, v[20:21]
	v_lshl_add_u64 v[20:21], v[20:21], 0, v[80:81]
	v_sub_f32_e32 v25, v25, v33
	v_sub_f32_e32 v24, v24, v32
	v_add_co_u32_e32 v20, vcc, 0x400000, v20
	v_cvt_pk_bf16_f32 v22, v27, v26
	v_cvt_pk_bf16_f32 v24, v24, v25
	v_cvt_pk_bf16_f32 v25, v29, v28
	v_addc_co_u32_e32 v21, vcc, 0, v21, vcc
	global_store_dwordx4 v[20:21], v[22:25], off offset:1024 sc1
